# mixer transpose loops and GLA loop: loop-top vmcnt(0) removed (only stores outstanding); GLA loop pinned at its better code placement with unreachable padding
# speedup vs baseline: 1.0047x; 1.0047x over previous
; #define BAR_LDS() do { asm volatile("s_waitcnt lgkmcnt(0)" ::: "memory"); __builtin_amdgcn_s_barrier(); asm volatile("" ::: "memory"); } while (0)
; __device__ __forceinline__ void gla_item(const Params& p, unsigned char* sm, int h, int job0, int jobstride, int nchunks, int tok0, int nvalid, const float* s_init, float* s_out, const int TIDX) {
;     const int tid = TIDX, w = __builtin_amdgcn_readfirstlane(tid >> 6), lane = tid & 63, r16 = lane & 15, g = lane >> 4;
;     unsigned char* QEl = sm; unsigned char* KEl = sm + 17408; unsigned char* KLl = sm + 34816; unsigned char* VTl = sm + 53248; unsigned char* AMl = sm + 90112;
;     float* EBl = (float*)(sm + 99328); float* SSQ = (float*)(sm + 99840); float* RSl = (float*)(sm + 101888); unsigned char* OTl = sm + 102400; float* GNl = (float*)(sm + 136192);
;     const bf16_t* QEg = (const bf16_t*)(p.ws + WS_QE); const bf16_t* KEg = (const bf16_t*)(p.ws + WS_KE); const bf16_t* KLg = (const bf16_t*)(p.ws + WS_KLT);
;     const bf16_t* VTg = (const bf16_t*)(p.ws + WS_VTG); const float* EBg = (const float*)(p.ws + WS_EBL); const bf16_t* GRg = (const bf16_t*)(p.ws + WS_GR);
;     bf16_t* CAT = (bf16_t*)(p.ws + WS_ABUF);
;     f32x4 S[8][2];
; #pragma unroll
;     for (int db = 0; db < 8; ++db) { S[db][0] = (f32x4){0.f, 0.f, 0.f, 0.f}; S[db][1] = (f32x4){0.f, 0.f, 0.f, 0.f}; }
;     if (s_init) {
;         const float* sp = s_init + (size_t)(4 * g) * 256 + 32 * w + r16;
; #pragma unroll
;         for (int db = 0; db < 8; ++db) {
; #pragma unroll
;             for (int j = 0; j < 4; ++j) { S[db][0][j] = sp[j * 256]; S[db][1][j] = sp[j * 256 + 16]; }
;             sp += 16 * 256; asm volatile("" : "+v"(sp));
;         }
;     }
;     u32x4 pq[2], pk[2], pl[2], pv[4]; f32x4 pe;
;     ...
;     BAR_LDS();
;     GLA_LOAD(job0, tok0);
;     GLA_STORE();
;     if (tid < 64) *(f32x4*)(GNl + tid * 4) = *(const f32x4*)(p.in[16] + tid * 4);
;     BAR_LDS();
.LBB0_124:
	s_or_b64 exec, exec, s[10:11]
	s_ashr_i32 s10, s12, 3
	s_and_b32 s10, s10, -16
	v_lshlrev_b32_e32 v124, 2, v117
	v_or_b32_e32 v0, s10, v118
	v_or_b32_e32 v125, s10, v124
	v_readlane_b32 s10, v255, 55
	v_readlane_b32 s11, v255, 56
	s_lshl_b32 s90, s13, 5
	s_lshl_b32 s13, s16, 9
	v_lshl_add_u64 v[180:181], v[114:115], 2, s[10:11]
	v_readlane_b32 s10, v255, 41
	s_add_u32 s10, s10, s13
	v_readlane_b32 s11, v255, 42
	s_addc_u32 s11, s11, 0
	s_andn2_b32 s12, s12, 63
	v_mul_lo_u32 v0, v0, s74
	s_lshl_b32 s14, s12, 2
	v_readlane_b32 s15, v254, 10
	v_add_u32_e32 v121, 0, v0
	v_lshlrev_b32_e32 v0, 3, v117
	s_add_i32 s83, s15, s14
	v_readlane_b32 s14, v254, 12
	v_add_u32_e32 v126, 0, v0
	v_readlane_b32 s38, v254, 11
	s_add_i32 s12, s14, s12
	v_add_u32_e32 v210, v126, v0
	v_and_b32_e32 v0, 0xf8, v112
	v_add_u32_e32 v211, s15, v114
	v_add_u32_e32 v212, s38, v114
	v_lshl_add_u32 v112, v118, 1, s12
	v_and_b32_e32 v114, 31, v116
	s_add_i32 s12, 0, 0x21400
	v_lshl_add_u32 v213, v114, 5, s12
	v_readlane_b32 s12, v255, 36
	v_lshlrev_b32_e32 v0, 1, v0
	s_add_u32 s12, s12, s13
	v_readlane_b32 s13, v255, 43
	v_lshl_add_u64 v[182:183], s[10:11], 0, v[0:1]
	v_lshlrev_b32_e32 v0, 4, v114
	s_addc_u32 s13, s13, 0
	v_and_or_b32 v122, s90, 32, v118
	v_readlane_b32 s20, v254, 9
	v_add_u32_e32 v128, s14, v0
	v_lshl_add_u64 v[184:185], s[12:13], 0, v[0:1]
	v_or_b32_e32 v0, 1, v125
	v_or_b32_e32 v130, 2, v125
	v_or_b32_e32 v131, 3, v125
	v_lshlrev_b32_e32 v209, 4, v117
	v_mad_u32_u24 v123, v122, s74, 0
	v_or_b32_e32 v127, s90, v118
	v_lshl_add_u32 v114, v122, 1, s20
	v_cmp_gt_i32_e64 s[12:13], v122, v125
	s_movk_i32 s28, 0x90
	v_cmp_gt_i32_e64 s[14:15], v122, v0
	v_cmp_gt_i32_e64 s[16:17], v122, v130
	v_cmp_gt_i32_e64 s[18:19], v122, v131
	v_or_b32_e32 v122, 16, v122
	v_ashrrev_i32_e32 v116, 5, v116
	v_ashrrev_i32_e32 v113, 5, v113
	v_ashrrev_i32_e32 v119, 5, v119
	v_ashrrev_i32_e32 v120, 5, v120
	v_or_b32_e32 v124, 1, v124
	s_waitcnt lgkmcnt(0)
	s_barrier
	v_add_u32_e32 v115, s20, v209
	v_mul_lo_u32 v129, v125, s28
	v_lshl_add_u32 v132, v122, 1, s20
	v_cmp_gt_i32_e64 s[20:21], v122, v125
	v_mul_lo_u32 v125, v127, s28
	v_cmp_gt_i32_e64 s[28:29], s36, v116
	v_cmp_gt_i32_e64 s[30:31], s36, v113
	v_cmp_gt_i32_e64 s[34:35], s36, v119
	v_cmp_gt_i32_e64 s[36:37], s36, v120
	v_add_u32_e32 v214, s38, v209
	v_lshl_add_u32 v215, v124, 2, s38
	s_movk_i32 s38, 0x210
	v_cmp_eq_u32_e64 s[10:11], 0, v118
	v_cmp_gt_i32_e64 s[22:23], v122, v0
	v_cmp_gt_i32_e64 s[24:25], v122, v130
	v_cmp_gt_i32_e64 s[26:27], v122, v131
	v_mul_u32_u24_e32 v122, 0x110, v118
	v_mul_u32_u24_e32 v0, 0x90, v118
	v_cndmask_b32_e64 v118, 0, v116, s[28:29]
	v_cndmask_b32_e64 v127, 0, v113, s[30:31]
	v_cndmask_b32_e64 v130, 0, v119, s[34:35]
	v_cndmask_b32_e64 v131, 0, v120, s[36:37]
	v_mul_u32_u24_e32 v117, 0x840, v117
	v_mul_u32_u24_e32 v124, 0x210, v124
	v_mul_lo_u32 v133, v116, s38
	v_mul_lo_u32 v134, v113, s38
	v_mul_lo_u32 v135, v119, s38
	v_mul_lo_u32 v136, v120, s38
	s_mov_b32 s91, 1
	s_mov_b32 s81, 0
	s_add_i32 s96, s96, 4
	s_lshl_b32 s84, s45, 6
	v_add_u32_e32 v216, s98, v116
	v_add_u32_e32 v217, s98, v113
	v_add_u32_e32 v218, s98, v119
	v_add_u32_e32 v219, s98, v120
	v_add_u32_e32 v220, s98, v131
	v_add_u32_e32 v221, s98, v130
	v_add_u32_e32 v222, s98, v127
	v_add_u32_e32 v223, s98, v118
	v_add_u32_e32 v224, v121, v209
	v_add_u32_e32 v225, v123, v209
	v_add_u32_e32 v226, v114, v129
	v_add_u32_e32 v227, v132, v129
	v_add_u32_e32 v228, v126, v122
	v_add_u32_e32 v229, v210, v125
	v_add_u32_e32 v230, v115, v0
	v_add_u32_e32 v231, v112, v117
	v_add_u32_e32 v232, v112, v124
	v_add_u32_e32 v233, v128, v133
	v_add_u32_e32 v234, v128, v134
	v_add_u32_e32 v235, v128, v135
	v_add_u32_e32 v236, v128, v136
	s_branch .LBB0_127
	s_nop 0
	s_nop 0
	s_nop 0
	s_nop 0
	s_nop 0
	s_nop 0
	s_nop 0
	s_nop 0
	s_nop 0
	s_nop 0
	s_nop 0
	s_nop 0
	s_nop 0

; __device__ __forceinline__ void gla_item(const Params& p, unsigned char* sm, int h, int job0, int jobstride, int nchunks, int tok0, int nvalid, const float* s_init, float* s_out, const int TIDX) {
;     ...
;     for (int ci = 0; ci < nchunks; ++ci) {
;         const int t0 = tok0 + ci * 64;
;         {
;             const int ib = w >> 1;
;             bf16x8 Aa[4], Ba[2][4];
; #pragma unroll
;             for (int ks = 0; ks < 4; ++ks) {
;                 Aa[ks] = *(const bf16x8*)(QEl + (16 * ib + r16) * 272 + (32 * ks + 8 * g) * 2);
;                 Ba[0][ks] = *(const bf16x8*)(KEl + (16 * (2 * (w & 1)) + r16) * 272 + (32 * ks + 8 * g) * 2);
;                 Ba[1][ks] = *(const bf16x8*)(KEl + (16 * (2 * (w & 1) + 1) + r16) * 272 + (32 * ks + 8 * g) * 2);
;             }
;             __builtin_amdgcn_sched_barrier(0);
; #pragma unroll
;             for (int jbi = 0; jbi < 2; ++jbi) {
;                 const int jb = 2 * (w & 1) + jbi; f32x4 acc = (f32x4){0.f, 0.f, 0.f, 0.f};
; #pragma unroll
;                 for (int ks = 0; ks < 4; ++ks) acc = MFMA16(Aa[ks], Ba[jbi][ks], acc);
; #pragma unroll
;                 for (int j = 0; j < 4; ++j) { const int i = 16 * ib + 4 * g + j, jj = 16 * jb + r16; const float v = jj <= i ? acc[j] : 0.f;
;                     *(bf16_t*)(AMl + i * 144 + jj * 2) = (bf16_t)(pk2(v, 0.f) & 0xffffu); }
;             }
;             __builtin_amdgcn_sched_barrier(0);
;         }
;         f32x4 o[4][2];
; #pragma unroll
;         for (int ib = 0; ib < 4; ++ib) { o[ib][0] = (f32x4){0.f, 0.f, 0.f, 0.f}; o[ib][1] = (f32x4){0.f, 0.f, 0.f, 0.f}; }
; #pragma unroll
;         for (int ks = 0; ks < 4; ++ks) {
;             bf16x8 Sf[2];
; #pragma unroll
;             for (int eb = 0; eb < 2; ++eb) {
;                 u32x4 t; t.x = pk2(S[2 * ks][eb][0], S[2 * ks][eb][1]); t.y = pk2(S[2 * ks][eb][2], S[2 * ks][eb][3]);
;                 t.z = pk2(S[2 * ks + 1][eb][0], S[2 * ks + 1][eb][1]); t.w = pk2(S[2 * ks + 1][eb][2], S[2 * ks + 1][eb][3]);
;                 Sf[eb] = __builtin_bit_cast(bf16x8, t);
;             }
;             bf16x8 Aq[4];
; #pragma unroll
;             for (int ib = 0; ib < 4; ++ib) {
;                 const u32x2 a0 = *(const u32x2*)(QEl + (16 * ib + r16) * 272 + (32 * ks + 4 * g) * 2);
;                 const u32x2 a1 = *(const u32x2*)(QEl + (16 * ib + r16) * 272 + (32 * ks + 16 + 4 * g) * 2);
.LBB0_127:
	ds_read_b128 v[112:115], v224
	ds_read_b128 v[116:119], v224 offset:64
	ds_read_b128 v[120:123], v225 offset:17408
	ds_read_b128 v[124:127], v225 offset:17472
	ds_read_b128 v[128:131], v225 offset:21760
	ds_read_b128 v[132:135], v225 offset:21824
	ds_read_b128 v[136:139], v224 offset:128
	ds_read_b128 v[140:143], v224 offset:192
	ds_read_b128 v[144:147], v225 offset:17536
	ds_read_b128 v[148:151], v225 offset:17600
	ds_read_b128 v[152:155], v225 offset:21888
	ds_read_b128 v[156:159], v225 offset:21952
	s_waitcnt lgkmcnt(0)
	v_mfma_f32_16x16x32_bf16 v[120:123], v[112:115], v[120:123], 0
	v_mfma_f32_16x16x32_bf16 v[112:115], v[112:115], v[128:131], 0
	v_mfma_f32_16x16x32_bf16 v[112:115], v[116:119], v[132:135], v[112:115]
	v_mfma_f32_16x16x32_bf16 v[120:123], v[116:119], v[124:127], v[120:123]
	v_mfma_f32_16x16x32_bf16 v[112:115], v[136:139], v[152:155], v[112:115]
	v_mfma_f32_16x16x32_bf16 v[120:123], v[136:139], v[144:147], v[120:123]
	v_mfma_f32_16x16x32_bf16 v[112:115], v[140:143], v[156:159], v[112:115]
	v_mfma_f32_16x16x32_bf16 v[120:123], v[140:143], v[148:151], v[120:123]
	s_nop 6
	v_cndmask_b32_e64 v112, v112, 0, s[20:21]
	v_cvt_pk_bf16_f32 v112, v112, v1
	ds_write_b16 v227, v112
	v_cndmask_b32_e64 v112, v113, 0, s[22:23]
	v_cvt_pk_bf16_f32 v112, v112, v1
	v_cndmask_b32_e64 v120, v120, 0, s[12:13]
	v_cndmask_b32_e64 v116, v122, 0, s[16:17]
	ds_write_b16 v227, v112 offset:144
	v_cndmask_b32_e64 v112, v114, 0, s[24:25]
	v_cvt_pk_bf16_f32 v120, v120, v1
	v_cvt_pk_bf16_f32 v116, v116, v1
	v_cvt_pk_bf16_f32 v112, v112, v1
	ds_write_b16 v226, v120
	v_cndmask_b32_e64 v120, v121, 0, s[14:15]
	ds_write_b16 v226, v116 offset:288
	v_cndmask_b32_e64 v116, v123, 0, s[18:19]
	ds_write_b16 v227, v112 offset:288
	v_cndmask_b32_e64 v112, v115, 0, s[26:27]
	v_cvt_pk_bf16_f32 v120, v120, v1
	ds_write_b16 v226, v120 offset:144
	v_cvt_pk_bf16_f32 v116, v116, v1
	ds_write_b16 v226, v116 offset:432
	v_cvt_pk_bf16_f32 v112, v112, v1
	ds_write_b16 v227, v112 offset:432
	v_add_u32_e32 v237, 0x1000, v228
	v_add_u32_e32 v238, 0x2000, v228
	v_add_u32_e32 v239, 0x3000, v228
	ds_read2_b64 v[116:119], v228 offset1:4
	ds_read2_b64 v[120:123], v237 offset0:32 offset1:36
	ds_read2_b64 v[124:127], v238 offset0:64 offset1:68
	ds_read2_b64 v[128:131], v239 offset0:96 offset1:100
	v_cvt_pk_bf16_f32 v112, v4, v5
	v_cvt_pk_bf16_f32 v113, v6, v7
	v_cvt_pk_bf16_f32 v114, v12, v13
	v_cvt_pk_bf16_f32 v115, v14, v15
	v_cvt_pk_bf16_f32 v132, v8, v9
	v_cvt_pk_bf16_f32 v133, v10, v11
	v_cvt_pk_bf16_f32 v134, v16, v17
	v_cvt_pk_bf16_f32 v135, v18, v19
	s_waitcnt lgkmcnt(3)
	v_mfma_f32_16x16x32_bf16 v[136:139], v[116:119], v[112:115], 0
	v_mfma_f32_16x16x32_bf16 v[116:119], v[116:119], v[132:135], 0
	s_waitcnt lgkmcnt(2)
	v_mfma_f32_16x16x32_bf16 v[140:143], v[120:123], v[112:115], 0
	v_mfma_f32_16x16x32_bf16 v[120:123], v[120:123], v[132:135], 0
	s_waitcnt lgkmcnt(1)
	v_mfma_f32_16x16x32_bf16 v[144:147], v[124:127], v[112:115], 0
	v_mfma_f32_16x16x32_bf16 v[124:127], v[124:127], v[132:135], 0
	s_waitcnt lgkmcnt(0)
	v_mfma_f32_16x16x32_bf16 v[112:115], v[128:131], v[112:115], 0
	v_mfma_f32_16x16x32_bf16 v[128:131], v[128:131], v[132:135], 0
	ds_read2_b64 v[148:151], v228 offset0:8 offset1:12
	ds_read2_b64 v[152:155], v237 offset0:40 offset1:44
	ds_read2_b64 v[156:159], v238 offset0:72 offset1:76
	ds_read2_b64 v[160:163], v239 offset0:104 offset1:108
	v_cvt_pk_bf16_f32 v132, v20, v21
	v_cvt_pk_bf16_f32 v133, v22, v23
	v_cvt_pk_bf16_f32 v134, v28, v29
	v_cvt_pk_bf16_f32 v135, v30, v31
	v_cvt_pk_bf16_f32 v164, v24, v25
	v_cvt_pk_bf16_f32 v165, v26, v27
	v_cvt_pk_bf16_f32 v166, v32, v33
	v_cvt_pk_bf16_f32 v167, v34, v35
	s_waitcnt lgkmcnt(3)
	v_mfma_f32_16x16x32_bf16 v[136:139], v[148:151], v[132:135], v[136:139]
	v_mfma_f32_16x16x32_bf16 v[116:119], v[148:151], v[164:167], v[116:119]
	s_waitcnt lgkmcnt(2)
	v_mfma_f32_16x16x32_bf16 v[140:143], v[152:155], v[132:135], v[140:143]
	v_mfma_f32_16x16x32_bf16 v[120:123], v[152:155], v[164:167], v[120:123]
	s_waitcnt lgkmcnt(1)
	v_mfma_f32_16x16x32_bf16 v[144:147], v[156:159], v[132:135], v[144:147]
	v_mfma_f32_16x16x32_bf16 v[124:127], v[156:159], v[164:167], v[124:127]
	s_waitcnt lgkmcnt(0)
	v_mfma_f32_16x16x32_bf16 v[112:115], v[160:163], v[132:135], v[112:115]
	v_mfma_f32_16x16x32_bf16 v[128:131], v[160:163], v[164:167], v[128:131]
	ds_read2_b64 v[148:151], v228 offset0:16 offset1:20
	ds_read2_b64 v[152:155], v237 offset0:48 offset1:52
	ds_read2_b64 v[156:159], v238 offset0:80 offset1:84
	ds_read2_b64 v[160:163], v239 offset0:112 offset1:116
	v_cvt_pk_bf16_f32 v132, v36, v37
	v_cvt_pk_bf16_f32 v133, v38, v39
	v_cvt_pk_bf16_f32 v134, v44, v45
	v_cvt_pk_bf16_f32 v135, v46, v47
	v_cvt_pk_bf16_f32 v164, v40, v41
	v_cvt_pk_bf16_f32 v165, v42, v43
	v_cvt_pk_bf16_f32 v166, v48, v49
	v_cvt_pk_bf16_f32 v167, v50, v51
	s_waitcnt lgkmcnt(3)
	v_mfma_f32_16x16x32_bf16 v[136:139], v[148:151], v[132:135], v[136:139]
	v_mfma_f32_16x16x32_bf16 v[116:119], v[148:151], v[164:167], v[116:119]
	s_waitcnt lgkmcnt(2)
	v_mfma_f32_16x16x32_bf16 v[140:143], v[152:155], v[132:135], v[140:143]
	v_mfma_f32_16x16x32_bf16 v[120:123], v[152:155], v[164:167], v[120:123]
	s_waitcnt lgkmcnt(1)
	v_mfma_f32_16x16x32_bf16 v[124:127], v[156:159], v[164:167], v[124:127]
	s_waitcnt lgkmcnt(0)
	v_mfma_f32_16x16x32_bf16 v[112:115], v[160:163], v[132:135], v[112:115]
	v_mfma_f32_16x16x32_bf16 v[128:131], v[160:163], v[164:167], v[128:131]
	v_mfma_f32_16x16x32_bf16 v[152:155], v[156:159], v[132:135], v[144:147]
	ds_read2_b64 v[148:151], v228 offset0:24 offset1:28
	ds_read2_b64 v[156:159], v237 offset0:56 offset1:60
	ds_read2_b64 v[160:163], v238 offset0:88 offset1:92
	ds_read2_b64 v[164:167], v239 offset0:120 offset1:124
	v_cvt_pk_bf16_f32 v132, v52, v53
	v_cvt_pk_bf16_f32 v133, v54, v55
	v_cvt_pk_bf16_f32 v134, v60, v61
	v_cvt_pk_bf16_f32 v135, v62, v63
	v_cvt_pk_bf16_f32 v238, v56, v57
	v_cvt_pk_bf16_f32 v239, v58, v59
	v_cvt_pk_bf16_f32 v240, v64, v65
	v_cvt_pk_bf16_f32 v241, v66, v67
	s_waitcnt lgkmcnt(3)
; #define MFMA16(a, b, c) __builtin_amdgcn_mfma_f32_16x16x32_bf16((a), (b), (c), 0, 0, 0)
; __device__ __forceinline__ void gla_item(const Params& p, unsigned char* sm, int h, int job0, int jobstride, int nchunks, int tok0, int nvalid, const float* s_init, float* s_out, const int TIDX) {
;     ...
;         bf16x8 Vf[2][2];
; #pragma unroll
;         for (int ks = 0; ks < 2; ++ks)
; #pragma unroll
;             for (int eb = 0; eb < 2; ++eb) Vf[ks][eb] = *(const bf16x8*)(VTl + (32 * w + 16 * eb + r16) * 144 + (32 * ks + 8 * g) * 2);
; #pragma unroll
;         for (int dp = 0; dp < 4; ++dp) {
;             bf16x8 Ak[2][2]; f32x4 e4[2];
; #pragma unroll
;             for (int q = 0; q < 2; ++q) { const int db = 2 * dp + q; e4[q] = *(const f32x4*)(EBl + 16 * db + 4 * g);
; #pragma unroll
;                 for (int ks = 0; ks < 2; ++ks) Ak[q][ks] = *(const bf16x8*)(KLl + (16 * db + r16) * 144 + (32 * ks + 8 * g) * 2); }
;             __builtin_amdgcn_sched_barrier(0);
; #pragma unroll
;             for (int q = 0; q < 2; ++q) { const int db = 2 * dp + q;
;                 S[db][0] = S[db][0] * e4[q]; S[db][1] = S[db][1] * e4[q];
; #pragma unroll
;                 for (int ks = 0; ks < 2; ++ks) { S[db][0] = MFMA16(Ak[q][ks], Vf[ks][0], S[db][0]); S[db][1] = MFMA16(Ak[q][ks], Vf[ks][1], S[db][1]); } }
;             __builtin_amdgcn_sched_barrier(0);
;         }
;         __builtin_amdgcn_sched_barrier(0);
;         if (ci + 1 < nchunks) GLA_LOAD(job0 + (ci + 1) * jobstride, t0 + 64);
	v_mfma_f32_16x16x32_bf16 v[144:147], v[148:151], v[132:135], v[136:139]
	v_mfma_f32_16x16x32_bf16 v[148:151], v[148:151], v[238:241], v[116:119]
	s_waitcnt lgkmcnt(2)
	v_mfma_f32_16x16x32_bf16 v[136:139], v[156:159], v[132:135], v[140:143]
	v_mfma_f32_16x16x32_bf16 v[140:143], v[156:159], v[238:241], v[120:123]
	s_waitcnt lgkmcnt(1)
	v_mfma_f32_16x16x32_bf16 v[120:123], v[160:163], v[132:135], v[152:155]
	v_mfma_f32_16x16x32_bf16 v[124:127], v[160:163], v[238:241], v[124:127]
	s_waitcnt lgkmcnt(0)
	v_mfma_f32_16x16x32_bf16 v[112:115], v[164:167], v[132:135], v[112:115]
	v_mfma_f32_16x16x32_bf16 v[116:119], v[164:167], v[238:241], v[128:131]
	v_add_u32_e32 v152, 0, v209
	v_add_u32_e32 v195, v210, v0
	s_nop 0
	ds_read_b128 v[128:131], v229 offset:53248
	ds_read_b128 v[132:135], v229 offset:53312
	ds_read_b128 v[164:167], v229 offset:55552
	ds_read_b128 v[160:163], v229 offset:55616
	v_add_u32_e32 v237, 0x18400, v152
	ds_read_b128 v[152:155], v195 offset:34816
	ds_read_b128 v[156:159], v195 offset:34880
	ds_read_b128 v[238:241], v237
	ds_read_b128 v[242:245], v237 offset:64
	ds_read_b128 v[246:249], v195 offset:37120
	ds_read_b128 v[250:253], v195 offset:37184
	s_waitcnt lgkmcnt(3)
	v_pk_mul_f32 v[6:7], v[6:7], v[240:241]
	v_pk_mul_f32 v[4:5], v[4:5], v[238:239]
	v_pk_mul_f32 v[10:11], v[10:11], v[240:241]
	v_pk_mul_f32 v[8:9], v[8:9], v[238:239]
	s_waitcnt lgkmcnt(2)
	v_pk_mul_f32 v[14:15], v[14:15], v[244:245]
	v_pk_mul_f32 v[12:13], v[12:13], v[242:243]
	v_pk_mul_f32 v[18:19], v[18:19], v[244:245]
	v_pk_mul_f32 v[16:17], v[16:17], v[242:243]
	v_mfma_f32_16x16x32_bf16 v[4:7], v[152:155], v[128:131], v[4:7]
	v_mfma_f32_16x16x32_bf16 v[8:11], v[152:155], v[164:167], v[8:11]
	s_waitcnt lgkmcnt(1)
	v_mfma_f32_16x16x32_bf16 v[12:15], v[246:249], v[128:131], v[12:15]
	v_mfma_f32_16x16x32_bf16 v[16:19], v[246:249], v[164:167], v[16:19]
	v_mfma_f32_16x16x32_bf16 v[4:7], v[156:159], v[132:135], v[4:7]
	v_mfma_f32_16x16x32_bf16 v[8:11], v[156:159], v[160:163], v[8:11]
	s_waitcnt lgkmcnt(0)
	v_mfma_f32_16x16x32_bf16 v[12:15], v[250:253], v[132:135], v[12:15]
	v_mfma_f32_16x16x32_bf16 v[16:19], v[250:253], v[160:163], v[16:19]
	ds_read_b128 v[152:155], v195 offset:39424
	ds_read_b128 v[156:159], v195 offset:39488
	ds_read_b128 v[238:241], v237 offset:128
	ds_read_b128 v[242:245], v237 offset:192
	ds_read_b128 v[246:249], v195 offset:41728
	ds_read_b128 v[250:253], v195 offset:41792
	s_waitcnt lgkmcnt(3)
	v_pk_mul_f32 v[22:23], v[22:23], v[240:241]
	v_pk_mul_f32 v[20:21], v[20:21], v[238:239]
	v_pk_mul_f32 v[26:27], v[26:27], v[240:241]
	v_pk_mul_f32 v[24:25], v[24:25], v[238:239]
	s_waitcnt lgkmcnt(2)
	v_pk_mul_f32 v[30:31], v[30:31], v[244:245]
	v_pk_mul_f32 v[28:29], v[28:29], v[242:243]
	v_pk_mul_f32 v[34:35], v[34:35], v[244:245]
	v_pk_mul_f32 v[32:33], v[32:33], v[242:243]
	v_mfma_f32_16x16x32_bf16 v[20:23], v[152:155], v[128:131], v[20:23]
	v_mfma_f32_16x16x32_bf16 v[24:27], v[152:155], v[164:167], v[24:27]
	s_waitcnt lgkmcnt(1)
	v_mfma_f32_16x16x32_bf16 v[28:31], v[246:249], v[128:131], v[28:31]
	v_mfma_f32_16x16x32_bf16 v[32:35], v[246:249], v[164:167], v[32:35]
	v_mfma_f32_16x16x32_bf16 v[20:23], v[156:159], v[132:135], v[20:23]
	v_mfma_f32_16x16x32_bf16 v[24:27], v[156:159], v[160:163], v[24:27]
	s_waitcnt lgkmcnt(0)
	v_mfma_f32_16x16x32_bf16 v[28:31], v[250:253], v[132:135], v[28:31]
	v_mfma_f32_16x16x32_bf16 v[32:35], v[250:253], v[160:163], v[32:35]
	ds_read_b128 v[152:155], v195 offset:44032
	ds_read_b128 v[156:159], v195 offset:44096
	ds_read_b128 v[238:241], v237 offset:256
	ds_read_b128 v[242:245], v237 offset:320
	ds_read_b128 v[246:249], v195 offset:46336
	ds_read_b128 v[250:253], v195 offset:46400
	s_waitcnt lgkmcnt(3)
	v_pk_mul_f32 v[38:39], v[38:39], v[240:241]
	v_pk_mul_f32 v[36:37], v[36:37], v[238:239]
	v_pk_mul_f32 v[42:43], v[42:43], v[240:241]
	v_pk_mul_f32 v[40:41], v[40:41], v[238:239]
	s_waitcnt lgkmcnt(2)
	v_pk_mul_f32 v[46:47], v[46:47], v[244:245]
	v_pk_mul_f32 v[44:45], v[44:45], v[242:243]
	v_pk_mul_f32 v[50:51], v[50:51], v[244:245]
	v_pk_mul_f32 v[48:49], v[48:49], v[242:243]
	v_mfma_f32_16x16x32_bf16 v[36:39], v[152:155], v[128:131], v[36:39]
	v_mfma_f32_16x16x32_bf16 v[40:43], v[152:155], v[164:167], v[40:43]
	s_waitcnt lgkmcnt(1)
	v_mfma_f32_16x16x32_bf16 v[44:47], v[246:249], v[128:131], v[44:47]
	v_mfma_f32_16x16x32_bf16 v[48:51], v[246:249], v[164:167], v[48:51]
	v_mfma_f32_16x16x32_bf16 v[36:39], v[156:159], v[132:135], v[36:39]
	v_mfma_f32_16x16x32_bf16 v[40:43], v[156:159], v[160:163], v[40:43]
	s_waitcnt lgkmcnt(0)
	v_mfma_f32_16x16x32_bf16 v[44:47], v[250:253], v[132:135], v[44:47]
	v_mfma_f32_16x16x32_bf16 v[48:51], v[250:253], v[160:163], v[48:51]
	ds_read_b128 v[152:155], v195 offset:48640
	ds_read_b128 v[156:159], v195 offset:48704
	ds_read_b128 v[238:241], v237 offset:384
	ds_read_b128 v[242:245], v237 offset:448
	ds_read_b128 v[246:249], v195 offset:50944
	ds_read_b128 v[250:253], v195 offset:51008
	s_waitcnt lgkmcnt(3)
	v_pk_mul_f32 v[54:55], v[54:55], v[240:241]
	v_pk_mul_f32 v[52:53], v[52:53], v[238:239]
	v_pk_mul_f32 v[58:59], v[58:59], v[240:241]
	v_pk_mul_f32 v[56:57], v[56:57], v[238:239]
	s_waitcnt lgkmcnt(2)
	v_pk_mul_f32 v[62:63], v[62:63], v[244:245]
	v_pk_mul_f32 v[60:61], v[60:61], v[242:243]
	v_pk_mul_f32 v[66:67], v[66:67], v[244:245]
	v_pk_mul_f32 v[64:65], v[64:65], v[242:243]
	v_mfma_f32_16x16x32_bf16 v[52:55], v[152:155], v[128:131], v[52:55]
	v_mfma_f32_16x16x32_bf16 v[56:59], v[152:155], v[164:167], v[56:59]
	s_waitcnt lgkmcnt(1)
	v_mfma_f32_16x16x32_bf16 v[60:63], v[246:249], v[128:131], v[60:63]
	v_mfma_f32_16x16x32_bf16 v[64:67], v[246:249], v[164:167], v[64:67]
	v_mfma_f32_16x16x32_bf16 v[52:55], v[156:159], v[132:135], v[52:55]
	v_mfma_f32_16x16x32_bf16 v[56:59], v[156:159], v[160:163], v[56:59]
	s_waitcnt lgkmcnt(0)
	v_mfma_f32_16x16x32_bf16 v[60:63], v[250:253], v[132:135], v[60:63]
	v_mfma_f32_16x16x32_bf16 v[64:67], v[250:253], v[160:163], v[64:67]
	s_cmp_lt_u32 s91, s45
	s_cselect_b64 s[98:99], -1, 0
	s_cmp_ge_u32 s91, s45
	s_cbranch_scc1 .LBB0_131
	s_ashr_i32 s97, s96, 31
	s_lshl_b64 s[38:39], s[96:97], 14
	s_add_u32 vcc_lo, s0, s38
	s_addc_u32 vcc_hi, s3, s39
	s_add_u32 s74, s40, s38
	s_addc_u32 s75, s41, s39
	s_add_u32 s38, s79, s38
	s_addc_u32 s39, s80, s39
	v_lshl_add_u64 v[76:77], s[38:39], 0, v[2:3]
	v_lshl_add_u64 v[88:89], s[38:39], 0, v[174:175]
	s_lshl_b64 s[38:39], s[96:97], 15
	s_add_u32 s38, s4, s38
	s_addc_u32 s39, s5, s39
	v_lshl_add_u64 v[68:69], vcc, 0, v[2:3]
	v_lshl_add_u64 v[72:73], s[74:75], 0, v[2:3]
	v_lshl_add_u64 v[80:81], vcc, 0, v[174:175]
	v_lshl_add_u64 v[84:85], s[74:75], 0, v[174:175]
	v_lshl_add_u64 v[92:93], s[38:39], 0, v[2:3]
	v_lshl_add_u64 v[96:97], s[38:39], 0, v[174:175]
	v_lshl_add_u64 v[100:101], v[176:177], 1, s[38:39]
	v_lshl_add_u64 v[104:105], v[178:179], 1, s[38:39]
	global_load_dwordx4 v[68:71], v[68:69], off
	s_nop 0
	global_load_dwordx4 v[72:75], v[72:73], off
	s_nop 0
	global_load_dwordx4 v[76:79], v[76:77], off
	s_nop 0
	global_load_dwordx4 v[80:83], v[80:81], off
	s_nop 0
	global_load_dwordx4 v[84:87], v[84:85], off
	s_nop 0
	global_load_dwordx4 v[88:91], v[88:89], off
	s_nop 0
	global_load_dwordx4 v[92:95], v[92:93], off
	s_nop 0
	global_load_dwordx4 v[96:99], v[96:97], off
	s_nop 0
	global_load_dwordx4 v[100:103], v[100:101], off
	s_nop 0
	global_load_dwordx4 v[104:107], v[104:105], off
	v_mov_b32_e32 v111, 0
	v_mov_b32_e32 v110, 0
	v_mov_b32_e32 v109, 0
	v_mov_b32_e32 v108, 0
	s_and_saveexec_b64 s[38:39], s[6:7]
	s_cbranch_execz .LBB0_130
	s_lshl_b64 s[74:75], s[96:97], 9
	v_lshl_add_u64 v[108:109], v[180:181], 0, s[74:75]
	global_load_dwordx4 v[108:111], v[108:109], off

; #define BAR_LDS() do { asm volatile("s_waitcnt lgkmcnt(0)" ::: "memory"); __builtin_amdgcn_s_barrier(); asm volatile("" ::: "memory"); } while (0)
; __device__ __forceinline__ void gla_item(const Params& p, unsigned char* sm, int h, int job0, int jobstride, int nchunks, int tok0, int nvalid, const float* s_init, float* s_out, const int TIDX) {
;     ...
;         BAR_LDS();
;         if (ci + 1 < nchunks) { GLA_STORE(); }
;         BAR_LDS();
;     }
.LBB0_173:
	s_or_b64 exec, exec, vcc
	s_branch .Lgla_next
	s_nop 0
	s_nop 0
	s_nop 0
	s_nop 0

; __device__ __forceinline__ void tr_matrix(const float* __restrict__ W, int K, int N, bf16_t* __restrict__ WT, int NBdst, int kind, const float* __restrict__ wg2,
;                                           float* scr, int it0, int it1, int nw, int lane) {
;     ...
;     for (int it = it0; it < (it1 < nitems ? it1 : nitems); it += nw) {
;         const int kb = it / NBdst, nb = it - kb * NBdst, k0 = kb * 64, n0 = nb * 32;
;         int nsrc = n0;
;         if (kind == 1) { const int pn = n0 >> 8, bj = (n0 >> 7) & 1, i = n0 & 127; nsrc = bj * DFF + pn * 128 + i; }
;         else if (kind == 2) nsrc = n0 < 3072 ? n0 : n0 + 16;
;         if (kind == 2 && n0 >= 5120) {
;             const int n = lane & 31;
;             float g2[16];
; #pragma unroll
;             for (int r = 0; r < 16; ++r) g2[r] = wg2[r * 512 + (n0 - 5120) + n];
; #pragma unroll 4
;             for (int i = 0; i < 32; ++i) {
;                 const int kk = 2 * i + (lane >> 5);
;                 const f32x4* wr = (const f32x4*)(W + (size_t)(k0 + kk) * N + 3072);
;                 const f32x4 a0 = wr[0], a1 = wr[1], a2 = wr[2], a3 = wr[3];
;                 float s = a0[0] * g2[0] + a0[1] * g2[1] + a0[2] * g2[2] + a0[3] * g2[3] + a1[0] * g2[4] + a1[1] * g2[5] + a1[2] * g2[6] + a1[3] * g2[7]
;                         + a2[0] * g2[8] + a2[1] * g2[9] + a2[2] * g2[10] + a2[3] * g2[11] + a3[0] * g2[12] + a3[1] * g2[13] + a3[2] * g2[14] + a3[3] * g2[15];
;                 scr[kk * 33 + n] = s;
;             }
;         } else {
;             float tv[32]; const float* wp = W + (size_t)(k0 + (lane >> 5)) * N + nsrc + (lane & 31);
; #pragma unroll
;             for (int i = 0; i < 32; ++i) tv[i] = wp[(size_t)(2 * i) * N];
.LBB0_183:
	v_ashrrev_i32_e32 v4, 31, v12
	v_lshrrev_b32_e32 v4, 26, v4
	v_add_u32_e32 v5, v12, v4
	v_and_b32_e32 v4, 0xffffffc0, v5
	v_lshlrev_b32_e32 v5, 5, v5
	v_or_b32_e32 v20, v4, v13
	v_and_b32_e32 v18, 0xfffff800, v5
	v_add_u32_e32 v5, s12, v16
	v_ashrrev_i32_e32 v21, 31, v20
	v_sub_u32_e32 v6, v5, v18
	v_lshlrev_b64 v[20:21], 13, v[20:21]
	s_waitcnt lgkmcnt(0)
	v_lshl_add_u64 v[20:21], s[60:61], 0, v[20:21]
	v_ashrrev_i32_e32 v7, 31, v6
	v_lshl_add_u64 v[6:7], v[6:7], 2, v[20:21]
	v_lshl_add_u64 v[6:7], v[6:7], 0, v[0:1]
	v_add_co_u32_e32 v20, vcc, s1, v6
	global_load_dword v5, v[6:7], off
	s_nop 0
	v_addc_co_u32_e32 v21, vcc, 0, v7, vcc
	global_load_dword v19, v[20:21], off
	v_add_co_u32_e32 v20, vcc, s16, v6
	v_add_u32_e32 v12, 8, v12
	s_nop 0
	v_addc_co_u32_e32 v21, vcc, 0, v7, vcc
	global_load_dword v22, v[20:21], off
	v_add_co_u32_e32 v20, vcc, s17, v6
	s_addk_i32 s12, 0x100
	s_nop 0
	v_addc_co_u32_e32 v21, vcc, 0, v7, vcc
	global_load_dword v23, v[20:21], off
	v_add_co_u32_e32 v20, vcc, s18, v6
	s_nop 1
	v_addc_co_u32_e32 v21, vcc, 0, v7, vcc
	global_load_dword v24, v[20:21], off
	v_add_co_u32_e32 v20, vcc, s82, v6
	s_nop 1
	v_addc_co_u32_e32 v21, vcc, 0, v7, vcc
	global_load_dword v25, v[20:21], off
	v_add_co_u32_e32 v20, vcc, s19, v6
	s_nop 1
	v_addc_co_u32_e32 v21, vcc, 0, v7, vcc
	global_load_dword v26, v[20:21], off
	v_add_co_u32_e32 v20, vcc, s20, v6
	s_nop 1
	v_addc_co_u32_e32 v21, vcc, 0, v7, vcc
	global_load_dword v27, v[20:21], off
	v_add_co_u32_e32 v20, vcc, s21, v6
	s_nop 1
	v_addc_co_u32_e32 v21, vcc, 0, v7, vcc
	global_load_dword v28, v[20:21], off
	v_add_co_u32_e32 v20, vcc, s22, v6
	s_nop 1
	v_addc_co_u32_e32 v21, vcc, 0, v7, vcc
	global_load_dword v29, v[20:21], off
	v_add_co_u32_e32 v20, vcc, s87, v6
	s_nop 1
	v_addc_co_u32_e32 v21, vcc, 0, v7, vcc
	global_load_dword v30, v[20:21], off
	v_add_co_u32_e32 v20, vcc, s23, v6
	s_nop 1
	v_addc_co_u32_e32 v21, vcc, 0, v7, vcc
	global_load_dword v31, v[20:21], off
	v_add_co_u32_e32 v20, vcc, s76, v6
	s_nop 1
	v_addc_co_u32_e32 v21, vcc, 0, v7, vcc
	global_load_dword v32, v[20:21], off
	v_add_co_u32_e32 v20, vcc, s73, v6
	s_nop 1
	v_addc_co_u32_e32 v21, vcc, 0, v7, vcc
	global_load_dword v33, v[20:21], off
	v_add_co_u32_e32 v20, vcc, s86, v6
	s_nop 1
	v_addc_co_u32_e32 v21, vcc, 0, v7, vcc
	global_load_dword v34, v[20:21], off
	v_add_co_u32_e32 v20, vcc, s78, v6
	s_nop 1
	v_addc_co_u32_e32 v21, vcc, 0, v7, vcc
	global_load_dword v35, v[20:21], off
	v_add_co_u32_e32 v20, vcc, s77, v6
	s_nop 1
	v_addc_co_u32_e32 v21, vcc, 0, v7, vcc
	global_load_dword v36, v[20:21], off
	v_add_co_u32_e32 v20, vcc, s13, v6
	s_nop 1
	v_addc_co_u32_e32 v21, vcc, 0, v7, vcc
	global_load_dword v37, v[20:21], off
	v_add_co_u32_e32 v20, vcc, s24, v6
	s_nop 1
	v_addc_co_u32_e32 v21, vcc, 0, v7, vcc
	global_load_dword v38, v[20:21], off
	v_add_co_u32_e32 v20, vcc, s25, v6
	s_nop 1
	v_addc_co_u32_e32 v21, vcc, 0, v7, vcc
	global_load_dword v39, v[20:21], off
	v_add_co_u32_e32 v20, vcc, s33, v6
	s_nop 1
	v_addc_co_u32_e32 v21, vcc, 0, v7, vcc
	global_load_dword v40, v[20:21], off
	v_add_co_u32_e32 v20, vcc, s26, v6
	s_nop 1
	v_addc_co_u32_e32 v21, vcc, 0, v7, vcc
	global_load_dword v41, v[20:21], off
	v_add_co_u32_e32 v20, vcc, s27, v6
	s_nop 1
	v_addc_co_u32_e32 v21, vcc, 0, v7, vcc
	global_load_dword v42, v[20:21], off
	v_add_co_u32_e32 v20, vcc, s28, v6
	s_nop 1
	v_addc_co_u32_e32 v21, vcc, 0, v7, vcc
	global_load_dword v43, v[20:21], off
	v_add_co_u32_e32 v20, vcc, s29, v6
	s_nop 1
	v_addc_co_u32_e32 v21, vcc, 0, v7, vcc
	global_load_dword v44, v[20:21], off
	v_add_co_u32_e32 v20, vcc, s92, v6
	s_nop 1
	v_addc_co_u32_e32 v21, vcc, 0, v7, vcc
	global_load_dword v45, v[20:21], off
	v_add_co_u32_e32 v20, vcc, s30, v6
	s_nop 1
	v_addc_co_u32_e32 v21, vcc, 0, v7, vcc
	global_load_dword v46, v[20:21], off
	v_add_co_u32_e32 v20, vcc, s31, v6
	s_nop 1
	v_addc_co_u32_e32 v21, vcc, 0, v7, vcc
	global_load_dword v47, v[20:21], off
	v_add_co_u32_e32 v20, vcc, s34, v6
	s_nop 1
	v_addc_co_u32_e32 v21, vcc, 0, v7, vcc
	global_load_dword v48, v[20:21], off
	v_add_co_u32_e32 v20, vcc, s35, v6
	s_nop 1
	v_addc_co_u32_e32 v21, vcc, 0, v7, vcc
	global_load_dword v49, v[20:21], off
	v_add_co_u32_e32 v20, vcc, s85, v6
	s_nop 1
	v_addc_co_u32_e32 v21, vcc, 0, v7, vcc
	v_add_co_u32_e32 v6, vcc, s39, v6
	global_load_dword v20, v[20:21], off
	s_nop 0
	v_addc_co_u32_e32 v7, vcc, 0, v7, vcc
	global_load_dword v6, v[6:7], off
	s_waitcnt vmcnt(30)
; __device__ __forceinline__ unsigned pk2(float lo, float hi) { unsigned r; asm("v_cvt_pk_bf16_f32 %0, %1, %2" : "=v"(r) : "v"(lo), "v"(hi)); return r; }
; #define LDSWAIT() asm volatile("s_waitcnt lgkmcnt(0)" ::: "memory")
; __device__ __forceinline__ void tr_matrix(const float* __restrict__ W, int K, int N, bf16_t* __restrict__ WT, int NBdst, int kind, const float* __restrict__ wg2,
;                                           float* scr, int it0, int it1, int nw, int lane) {
;     ...
; #pragma unroll
;             for (int i = 0; i < 32; ++i) scr[(2 * i + (lane >> 5)) * 33 + (lane & 31)] = tv[i];
;         }
;         LDSWAIT();
;         const int c = lane & 7;
; #pragma unroll
;         for (int j = 0; j < 4; ++j) {
;             const int n = (lane >> 3) + 8 * j; const float* s = scr + (8 * c) * 33 + n;
;             u32x4 o; o.x = pk2(s[0], s[33]); o.y = pk2(s[66], s[99]); o.z = pk2(s[132], s[165]); o.w = pk2(s[198], s[231]);
;             *(u32x4*)(WT + (size_t)(n0 + n) * K + k0 + 8 * c) = o;
;         }
;         LDSWAIT();
	ds_write2_b32 v15, v5, v19 offset1:66
	s_waitcnt vmcnt(28)
	ds_write2_b32 v15, v22, v23 offset0:132 offset1:198
	v_add_u32_e32 v5, 0x400, v15
	s_waitcnt vmcnt(26)
	ds_write2_b32 v5, v24, v25 offset0:8 offset1:74
	s_waitcnt vmcnt(24)
	ds_write2_b32 v5, v26, v27 offset0:140 offset1:206
	v_add_u32_e32 v5, 0x800, v15
	s_waitcnt vmcnt(22)
	ds_write2_b32 v5, v28, v29 offset0:16 offset1:82
	s_waitcnt vmcnt(20)
	ds_write2_b32 v5, v30, v31 offset0:148 offset1:214
	v_add_u32_e32 v5, 0xc00, v15
	s_waitcnt vmcnt(18)
	ds_write2_b32 v5, v32, v33 offset0:24 offset1:90
	s_waitcnt vmcnt(16)
	ds_write2_b32 v5, v34, v35 offset0:156 offset1:222
	v_add_u32_e32 v5, 0x1000, v15
	s_waitcnt vmcnt(14)
	ds_write2_b32 v5, v36, v37 offset0:32 offset1:98
	s_waitcnt vmcnt(12)
	ds_write2_b32 v5, v38, v39 offset0:164 offset1:230
	v_add_u32_e32 v5, 0x1400, v15
	s_waitcnt vmcnt(10)
	ds_write2_b32 v5, v40, v41 offset0:40 offset1:106
	s_waitcnt vmcnt(8)
	ds_write2_b32 v5, v42, v43 offset0:172 offset1:238
	v_add_u32_e32 v5, 0x1800, v15
	s_waitcnt vmcnt(6)
	ds_write2_b32 v5, v44, v45 offset0:48 offset1:114
	s_waitcnt vmcnt(4)
	ds_write2_b32 v5, v46, v47 offset0:180 offset1:246
	v_add_u32_e32 v5, 0x1c00, v15
	s_waitcnt vmcnt(2)
	ds_write2_b32 v5, v48, v49 offset0:56 offset1:122
	s_waitcnt vmcnt(0)
	ds_write2_b32 v5, v20, v6 offset0:188 offset1:254
	s_waitcnt lgkmcnt(0)
	ds_read2_b32 v[22:23], v14 offset0:33 offset1:41
	ds_read2_b32 v[24:25], v14 offset1:8
	ds_read2_b32 v[26:27], v14 offset0:66 offset1:74
	ds_read2_b32 v[28:29], v14 offset0:99 offset1:107
	ds_read2_b32 v[30:31], v14 offset0:132 offset1:140
	ds_read2_b32 v[32:33], v14 offset0:165 offset1:173
	ds_read2_b32 v[34:35], v14 offset0:198 offset1:206
	ds_read2_b32 v[36:37], v14 offset0:231 offset1:239
	v_add_u32_e32 v19, v16, v17
	v_ashrrev_i32_e32 v5, 31, v4
	v_sub_u32_e32 v38, v19, v18
	v_lshl_add_u64 v[20:21], v[4:5], 1, v[2:3]
	v_add_u32_e32 v18, 0xffc3a000, v38
	v_mad_i64_i32 v[18:19], s[14:15], v18, s93, v[20:21]
	s_waitcnt lgkmcnt(6)
	v_cvt_pk_bf16_f32 v4, v24, v22
	s_waitcnt lgkmcnt(4)
	v_cvt_pk_bf16_f32 v5, v26, v28
	s_waitcnt lgkmcnt(2)
	v_cvt_pk_bf16_f32 v6, v30, v32
	s_waitcnt lgkmcnt(0)
	v_cvt_pk_bf16_f32 v7, v34, v36
	global_store_dwordx4 v[18:19], v[4:7], off
	v_add_u32_e32 v18, 0xffc3a008, v38
	v_mad_i64_i32 v[18:19], s[14:15], v18, s93, v[20:21]
	v_cvt_pk_bf16_f32 v4, v25, v23
	v_cvt_pk_bf16_f32 v5, v27, v29
	v_cvt_pk_bf16_f32 v6, v31, v33
	v_cvt_pk_bf16_f32 v7, v35, v37
	global_store_dwordx4 v[18:19], v[4:7], off
	ds_read2_b32 v[18:19], v14 offset0:16 offset1:24
	ds_read2_b32 v[22:23], v14 offset0:49 offset1:57
	ds_read2_b32 v[24:25], v14 offset0:82 offset1:90
	ds_read2_b32 v[26:27], v14 offset0:115 offset1:123
	ds_read2_b32 v[28:29], v14 offset0:148 offset1:156
	ds_read2_b32 v[30:31], v14 offset0:181 offset1:189
	ds_read2_b32 v[32:33], v14 offset0:214 offset1:222
	ds_read2_b32 v[34:35], v14 offset0:247 offset1:255
	s_waitcnt lgkmcnt(6)
	v_cvt_pk_bf16_f32 v4, v18, v22
	v_add_u32_e32 v18, 0xffc3a010, v38
	v_mad_i64_i32 v[36:37], s[14:15], v18, s93, v[20:21]
	v_add_u32_e32 v18, 0xffc3a018, v38
	s_waitcnt lgkmcnt(4)
	v_cvt_pk_bf16_f32 v5, v24, v26
	s_waitcnt lgkmcnt(2)
	v_cvt_pk_bf16_f32 v6, v28, v30
	s_waitcnt lgkmcnt(0)
	v_cvt_pk_bf16_f32 v7, v32, v34
	global_store_dwordx4 v[36:37], v[4:7], off
	v_cmp_le_i32_e32 vcc, s11, v12
	v_add_u32_e32 v17, 0x100, v17
	v_cvt_pk_bf16_f32 v4, v19, v23
	v_mad_i64_i32 v[18:19], s[14:15], v18, s93, v[20:21]
	v_cvt_pk_bf16_f32 v5, v25, v27
	v_cvt_pk_bf16_f32 v6, v29, v31
	v_cvt_pk_bf16_f32 v7, v33, v35
	global_store_dwordx4 v[18:19], v[4:7], off
	s_waitcnt lgkmcnt(0)
	s_or_b64 s[8:9], vcc, s[8:9]
	s_andn2_b64 exec, exec, s[8:9]
	s_cbranch_execnz .LBB0_183

; __device__ __forceinline__ void tr_matrix(const float* __restrict__ W, int K, int N, bf16_t* __restrict__ WT, int NBdst, int kind, const float* __restrict__ wg2,
;                                           float* scr, int it0, int it1, int nw, int lane) {
;     ...
;     for (int it = it0; it < (it1 < nitems ? it1 : nitems); it += nw) {
;         const int kb = it / NBdst, nb = it - kb * NBdst, k0 = kb * 64, n0 = nb * 32;
;         int nsrc = n0;
;         if (kind == 1) { const int pn = n0 >> 8, bj = (n0 >> 7) & 1, i = n0 & 127; nsrc = bj * DFF + pn * 128 + i; }
;         else if (kind == 2) nsrc = n0 < 3072 ? n0 : n0 + 16;
;         if (kind == 2 && n0 >= 5120) {
;             const int n = lane & 31;
;             float g2[16];
; #pragma unroll
;             for (int r = 0; r < 16; ++r) g2[r] = wg2[r * 512 + (n0 - 5120) + n];
; #pragma unroll 4
;             for (int i = 0; i < 32; ++i) {
;                 const int kk = 2 * i + (lane >> 5);
;                 const f32x4* wr = (const f32x4*)(W + (size_t)(k0 + kk) * N + 3072);
;                 const f32x4 a0 = wr[0], a1 = wr[1], a2 = wr[2], a3 = wr[3];
;                 float s = a0[0] * g2[0] + a0[1] * g2[1] + a0[2] * g2[2] + a0[3] * g2[3] + a1[0] * g2[4] + a1[1] * g2[5] + a1[2] * g2[6] + a1[3] * g2[7]
;                         + a2[0] * g2[8] + a2[1] * g2[9] + a2[2] * g2[10] + a2[3] * g2[11] + a3[0] * g2[12] + a3[1] * g2[13] + a3[2] * g2[14] + a3[3] * g2[15];
;                 scr[kk * 33 + n] = s;
;             }
;         } else {
;             float tv[32]; const float* wp = W + (size_t)(k0 + (lane >> 5)) * N + nsrc + (lane & 31);
; #pragma unroll
;             for (int i = 0; i < 32; ++i) tv[i] = wp[(size_t)(2 * i) * N];
.LBB0_188:
	v_add_u32_e32 v8, 8, v8
	v_mul_hi_i32 v4, v8, s11
	v_lshrrev_b32_e32 v5, 31, v4
	v_ashrrev_i32_e32 v4, 6, v4
	v_add_u32_e32 v4, v4, v5
	v_mad_i32_i24 v5, v4, s14, v8
	v_lshlrev_b32_e32 v16, 5, v5
	v_bfe_i32 v6, v8, 2, 1
	v_lshlrev_b32_e32 v5, 4, v5
	v_and_b32_e32 v6, 0x1580, v6
	v_and_b32_e32 v5, 0xffffff80, v5
	v_lshlrev_b32_e32 v4, 6, v4
	v_add_u32_e32 v5, v5, v6
	v_and_or_b32 v6, v16, s15, v5
	v_or_b32_e32 v5, v4, v12
	s_waitcnt lgkmcnt(0)
	v_mov_b64_e32 v[18:19], s[58:59]
	v_mad_i64_i32 v[18:19], s[12:13], v5, s24, v[18:19]
	v_ashrrev_i32_e32 v7, 31, v6
	v_lshl_add_u64 v[6:7], v[6:7], 2, v[18:19]
	v_lshl_add_u64 v[6:7], v[6:7], 0, v[0:1]
	v_add_co_u32_e32 v18, vcc, s25, v6
	global_load_dword v5, v[6:7], off
	s_nop 0
	v_addc_co_u32_e32 v19, vcc, 0, v7, vcc
	global_load_dword v17, v[18:19], off offset:2048
	v_add_co_u32_e32 v18, vcc, s26, v6
	s_nop 1
	v_addc_co_u32_e32 v19, vcc, 0, v7, vcc
	global_load_dword v20, v[18:19], off
	v_add_co_u32_e32 v18, vcc, s92, v6
	s_nop 1
	v_addc_co_u32_e32 v19, vcc, 0, v7, vcc
	global_load_dword v21, v[18:19], off offset:2048
	v_add_co_u32_e32 v18, vcc, s27, v6
	s_nop 1
	v_addc_co_u32_e32 v19, vcc, 0, v7, vcc
	global_load_dword v22, v[18:19], off
	v_add_co_u32_e32 v18, vcc, s28, v6
	s_nop 1
	v_addc_co_u32_e32 v19, vcc, 0, v7, vcc
	global_load_dword v23, v[18:19], off offset:2048
	v_add_co_u32_e32 v18, vcc, s29, v6
	s_nop 1
	v_addc_co_u32_e32 v19, vcc, 0, v7, vcc
	global_load_dword v24, v[18:19], off
	v_add_co_u32_e32 v18, vcc, s30, v6
	s_nop 1
	v_addc_co_u32_e32 v19, vcc, 0, v7, vcc
	global_load_dword v25, v[18:19], off offset:2048
	v_add_co_u32_e32 v18, vcc, s31, v6
	s_nop 1
	v_addc_co_u32_e32 v19, vcc, 0, v7, vcc
	global_load_dword v26, v[18:19], off
	v_add_co_u32_e32 v18, vcc, s34, v6
	s_nop 1
	v_addc_co_u32_e32 v19, vcc, 0, v7, vcc
	global_load_dword v27, v[18:19], off offset:2048
	v_add_co_u32_e32 v18, vcc, s35, v6
	s_nop 1
	v_addc_co_u32_e32 v19, vcc, 0, v7, vcc
	global_load_dword v28, v[18:19], off
	v_add_co_u32_e32 v18, vcc, s39, v6
	s_nop 1
	v_addc_co_u32_e32 v19, vcc, 0, v7, vcc
	global_load_dword v29, v[18:19], off offset:2048
	v_add_co_u32_e32 v18, vcc, s45, v6
	s_nop 1
	v_addc_co_u32_e32 v19, vcc, 0, v7, vcc
	global_load_dword v30, v[18:19], off
	v_add_co_u32_e32 v18, vcc, s81, v6
	s_nop 1
	v_addc_co_u32_e32 v19, vcc, 0, v7, vcc
	global_load_dword v31, v[18:19], off offset:2048
	v_add_co_u32_e32 v18, vcc, s90, v6
	s_nop 1
	v_addc_co_u32_e32 v19, vcc, 0, v7, vcc
	global_load_dword v32, v[18:19], off
	v_add_co_u32_e32 v18, vcc, s91, v6
	s_nop 1
	v_addc_co_u32_e32 v19, vcc, 0, v7, vcc
	global_load_dword v33, v[18:19], off offset:2048
	v_add_co_u32_e32 v18, vcc, s98, v6
	s_nop 1
	v_addc_co_u32_e32 v19, vcc, 0, v7, vcc
	global_load_dword v34, v[18:19], off
	v_add_co_u32_e32 v18, vcc, s99, v6
	s_nop 1
	v_addc_co_u32_e32 v19, vcc, 0, v7, vcc
	global_load_dword v35, v[18:19], off offset:2048
	v_add_co_u32_e32 v18, vcc, s84, v6
	s_nop 1
	v_addc_co_u32_e32 v19, vcc, 0, v7, vcc
	global_load_dword v36, v[18:19], off
	v_add_co_u32_e32 v18, vcc, s2, v6
	s_nop 1
	v_addc_co_u32_e32 v19, vcc, 0, v7, vcc
	global_load_dword v37, v[18:19], off offset:2048
	v_add_co_u32_e32 v18, vcc, s96, v6
	s_nop 1
	v_addc_co_u32_e32 v19, vcc, 0, v7, vcc
	global_load_dword v38, v[18:19], off
	v_add_co_u32_e32 v18, vcc, s74, v6
	s_nop 1
	v_addc_co_u32_e32 v19, vcc, 0, v7, vcc
	global_load_dword v39, v[18:19], off offset:2048
	v_add_co_u32_e32 v18, vcc, s36, v6
	s_nop 1
	v_addc_co_u32_e32 v19, vcc, 0, v7, vcc
	global_load_dword v40, v[18:19], off
	v_add_co_u32_e32 v18, vcc, s42, v6
	s_nop 1
	v_addc_co_u32_e32 v19, vcc, 0, v7, vcc
	global_load_dword v41, v[18:19], off offset:2048
	v_add_co_u32_e32 v18, vcc, s38, v6
	s_nop 1
	v_addc_co_u32_e32 v19, vcc, 0, v7, vcc
	global_load_dword v42, v[18:19], off
	v_add_co_u32_e32 v18, vcc, s37, v6
	s_nop 1
	v_addc_co_u32_e32 v19, vcc, 0, v7, vcc
	global_load_dword v43, v[18:19], off offset:2048
	v_add_co_u32_e32 v18, vcc, s75, v6
	s_nop 1
	v_addc_co_u32_e32 v19, vcc, 0, v7, vcc
	global_load_dword v44, v[18:19], off
	v_add_co_u32_e32 v18, vcc, s76, v6
	s_nop 1
	v_addc_co_u32_e32 v19, vcc, 0, v7, vcc
	global_load_dword v45, v[18:19], off offset:2048
	v_add_co_u32_e32 v18, vcc, s73, v6
	s_nop 1
	v_addc_co_u32_e32 v19, vcc, 0, v7, vcc
	global_load_dword v46, v[18:19], off
	v_add_co_u32_e32 v18, vcc, s86, v6
	s_nop 1
	v_addc_co_u32_e32 v19, vcc, 0, v7, vcc
	global_load_dword v47, v[18:19], off offset:2048
	v_add_co_u32_e32 v18, vcc, s77, v6
	s_nop 1
	v_addc_co_u32_e32 v19, vcc, 0, v7, vcc
	v_add_co_u32_e32 v6, vcc, s85, v6
	global_load_dword v18, v[18:19], off
	s_nop 0
	v_addc_co_u32_e32 v7, vcc, 0, v7, vcc
	global_load_dword v6, v[6:7], off offset:2048
	s_waitcnt vmcnt(30)
; __device__ __forceinline__ unsigned pk2(float lo, float hi) { unsigned r; asm("v_cvt_pk_bf16_f32 %0, %1, %2" : "=v"(r) : "v"(lo), "v"(hi)); return r; }
; #define LDSWAIT() asm volatile("s_waitcnt lgkmcnt(0)" ::: "memory")
; __device__ __forceinline__ void tr_matrix(const float* __restrict__ W, int K, int N, bf16_t* __restrict__ WT, int NBdst, int kind, const float* __restrict__ wg2,
;                                           float* scr, int it0, int it1, int nw, int lane) {
;     ...
; #pragma unroll
;             for (int i = 0; i < 32; ++i) scr[(2 * i + (lane >> 5)) * 33 + (lane & 31)] = tv[i];
;         }
;         LDSWAIT();
;         const int c = lane & 7;
; #pragma unroll
;         for (int j = 0; j < 4; ++j) {
;             const int n = (lane >> 3) + 8 * j; const float* s = scr + (8 * c) * 33 + n;
;             u32x4 o; o.x = pk2(s[0], s[33]); o.y = pk2(s[66], s[99]); o.z = pk2(s[132], s[165]); o.w = pk2(s[198], s[231]);
;             *(u32x4*)(WT + (size_t)(n0 + n) * K + k0 + 8 * c) = o;
;         }
;         LDSWAIT();
;     }
	ds_write2_b32 v9, v5, v17 offset1:66
	s_waitcnt vmcnt(28)
	ds_write2_b32 v9, v20, v21 offset0:132 offset1:198
	v_add_u32_e32 v5, 0x400, v9
	s_waitcnt vmcnt(26)
	ds_write2_b32 v5, v22, v23 offset0:8 offset1:74
	s_waitcnt vmcnt(24)
	ds_write2_b32 v5, v24, v25 offset0:140 offset1:206
	v_add_u32_e32 v5, 0x800, v9
	s_waitcnt vmcnt(22)
	ds_write2_b32 v5, v26, v27 offset0:16 offset1:82
	s_waitcnt vmcnt(20)
	ds_write2_b32 v5, v28, v29 offset0:148 offset1:214
	v_add_u32_e32 v5, 0xc00, v9
	s_waitcnt vmcnt(18)
	ds_write2_b32 v5, v30, v31 offset0:24 offset1:90
	s_waitcnt vmcnt(16)
	ds_write2_b32 v5, v32, v33 offset0:156 offset1:222
	v_add_u32_e32 v5, 0x1000, v9
	s_waitcnt vmcnt(14)
	ds_write2_b32 v5, v34, v35 offset0:32 offset1:98
	s_waitcnt vmcnt(12)
	ds_write2_b32 v5, v36, v37 offset0:164 offset1:230
	v_add_u32_e32 v5, 0x1400, v9
	s_waitcnt vmcnt(10)
	ds_write2_b32 v5, v38, v39 offset0:40 offset1:106
	s_waitcnt vmcnt(8)
	ds_write2_b32 v5, v40, v41 offset0:172 offset1:238
	v_add_u32_e32 v5, 0x1800, v9
	s_waitcnt vmcnt(6)
	ds_write2_b32 v5, v42, v43 offset0:48 offset1:114
	s_waitcnt vmcnt(4)
	ds_write2_b32 v5, v44, v45 offset0:180 offset1:246
	v_add_u32_e32 v5, 0x1c00, v9
	s_waitcnt vmcnt(2)
	ds_write2_b32 v5, v46, v47 offset0:56 offset1:122
	s_waitcnt vmcnt(0)
	ds_write2_b32 v5, v18, v6 offset0:188 offset1:254
	s_waitcnt lgkmcnt(0)
	ds_read2_b32 v[20:21], v11 offset0:33 offset1:41
	ds_read2_b32 v[22:23], v11 offset1:8
	ds_read2_b32 v[24:25], v11 offset0:66 offset1:74
	ds_read2_b32 v[26:27], v11 offset0:99 offset1:107
	ds_read2_b32 v[28:29], v11 offset0:132 offset1:140
	ds_read2_b32 v[30:31], v11 offset0:165 offset1:173
	ds_read2_b32 v[32:33], v11 offset0:198 offset1:206
	ds_read2_b32 v[34:35], v11 offset0:231 offset1:239
	v_or_b32_e32 v36, v16, v10
	v_ashrrev_i32_e32 v5, 31, v4
	v_ashrrev_i32_e32 v37, 31, v36
	v_lshl_add_u64 v[18:19], v[4:5], 1, v[2:3]
	v_lshlrev_b64 v[36:37], 12, v[36:37]
	s_waitcnt lgkmcnt(6)
	v_cvt_pk_bf16_f32 v4, v22, v20
	v_lshl_add_u64 v[36:37], v[18:19], 0, v[36:37]
	v_or_b32_e32 v20, v16, v13
	s_waitcnt lgkmcnt(4)
	v_cvt_pk_bf16_f32 v5, v24, v26
	s_waitcnt lgkmcnt(2)
	v_cvt_pk_bf16_f32 v6, v28, v30
	s_waitcnt lgkmcnt(0)
	v_cvt_pk_bf16_f32 v7, v32, v34
	global_store_dwordx4 v[36:37], v[4:7], off
	v_or_b32_e32 v36, v16, v14
	v_or_b32_e32 v16, v16, v15
	v_cvt_pk_bf16_f32 v4, v23, v21
	v_ashrrev_i32_e32 v21, 31, v20
	v_lshlrev_b64 v[20:21], 12, v[20:21]
	v_lshl_add_u64 v[20:21], v[18:19], 0, v[20:21]
	v_cvt_pk_bf16_f32 v5, v25, v27
	v_cvt_pk_bf16_f32 v6, v29, v31
	v_cvt_pk_bf16_f32 v7, v33, v35
	global_store_dwordx4 v[20:21], v[4:7], off
	ds_read2_b32 v[20:21], v11 offset0:16 offset1:24
	ds_read2_b32 v[22:23], v11 offset0:49 offset1:57
	ds_read2_b32 v[24:25], v11 offset0:82 offset1:90
	ds_read2_b32 v[26:27], v11 offset0:115 offset1:123
	ds_read2_b32 v[28:29], v11 offset0:148 offset1:156
	ds_read2_b32 v[30:31], v11 offset0:181 offset1:189
	ds_read2_b32 v[32:33], v11 offset0:214 offset1:222
	ds_read2_b32 v[34:35], v11 offset0:247 offset1:255
	v_ashrrev_i32_e32 v37, 31, v36
	v_ashrrev_i32_e32 v17, 31, v16
	v_lshlrev_b64 v[36:37], 12, v[36:37]
	v_lshlrev_b64 v[16:17], 12, v[16:17]
	s_waitcnt lgkmcnt(6)
	v_cvt_pk_bf16_f32 v4, v20, v22
	s_waitcnt lgkmcnt(4)
	v_cvt_pk_bf16_f32 v5, v24, v26
	s_waitcnt lgkmcnt(2)
	v_cvt_pk_bf16_f32 v6, v28, v30
	s_waitcnt lgkmcnt(0)
	v_cvt_pk_bf16_f32 v7, v32, v34
	v_lshl_add_u64 v[36:37], v[18:19], 0, v[36:37]
	v_lshl_add_u64 v[16:17], v[18:19], 0, v[16:17]
	global_store_dwordx4 v[36:37], v[4:7], off
	v_cmp_le_i32_e32 vcc, s10, v8
	s_or_b64 s[8:9], vcc, s[8:9]
	v_cvt_pk_bf16_f32 v4, v21, v23
	v_cvt_pk_bf16_f32 v5, v25, v27
	v_cvt_pk_bf16_f32 v6, v29, v31
	v_cvt_pk_bf16_f32 v7, v33, v35
	global_store_dwordx4 v[16:17], v[4:7], off
	s_waitcnt lgkmcnt(0)
	s_andn2_b64 exec, exec, s[8:9]
	s_cbranch_execnz .LBB0_188
	s_branch .LBB0_39
